# v100 + MLA fast path unrolled by ring stage (4 copies): loop-invariant K/V fragment bases, stage offsets as immediates, no per-tile stage arithmetic
# baseline (speedup 1.0000x reference)
.Lmla_fast:
	s_mov_b32 s42, s30
	s_and_b32 s34, s30, 3
	s_mul_i32 s8, s34, 0x6400
	v_add_u32_e32 v198, v143, v132
	v_add_u32_e32 v200, v144, v145
	v_add_u32_e32 v0, s8, v198
	v_add_u32_e32 v199, 0x6400, v198
	v_add_u32_e32 v200, 0x3400, v200
	ds_read_b128 v[194:197], v0
	ds_read_b128 v[150:153], v0 offset:32
	ds_read_b128 v[158:161], v0 offset:64
	ds_read_b128 v[162:165], v0 offset:96
	ds_read_b128 v[174:177], v0 offset:128
	ds_read_b128 v[178:181], v0 offset:160
	v_add_u32_e32 v201, 0x6400, v200
	s_cmp_eq_u32 s34, 1
	s_cbranch_scc1 .Lmla_fast_havek_c1
	s_cmp_eq_u32 s34, 2
	s_cbranch_scc1 .Lmla_fast_havek_c2
	s_cmp_eq_u32 s34, 3
	s_cbranch_scc1 .Lmla_fast_havek_c3
.Lmla_fast_havek_c0:
	s_add_i32 s34, s30, 2
	s_cmp_gt_u32 s34, s14
	s_cbranch_scc1 .Lmla_fast_d2_c0
	s_mov_b32 s34, 0xc800
	s_add_i32 s8, s34, s5
	s_mov_b32 m0, s8
	s_and_b64 vcc, exec, s[36:37]
	global_load_lds_dwordx4 v66, s[26:27]
	s_add_i32 m0, s8, 0x2000
	v_add_u32_e32 v66, v66, v134
	global_load_lds_dwordx4 v68, s[26:27]
	s_add_i32 m0, s8, 0x4000
	v_add_u32_e32 v68, v68, v136
	global_load_lds_dwordx4 v70, s[26:27]
	v_add_u32_e32 v70, v70, v138
	s_cbranch_vccnz .Lmla_fast_d2_c0
	s_add_i32 m0, s34, 0x6000
	s_nop 0
	global_load_lds_dwordx4 v72, s[26:27]
	v_add_u32_e32 v72, v72, v140
.Lmla_fast_d2_c0:
	s_cmp_gt_u32 s30, s13
	s_cbranch_scc1 .Lmla_fast_nodma_c0
	s_mov_b32 s34, 0x12c00
	s_add_i32 s8, s34, s5
	s_mov_b32 m0, s8
	s_and_b64 vcc, exec, s[36:37]
	global_load_lds_dwordx4 v66, s[26:27]
	s_add_i32 m0, s8, 0x2000
	v_add_u32_e32 v66, v66, v134
	global_load_lds_dwordx4 v68, s[26:27]
	s_add_i32 m0, s8, 0x4000
	v_add_u32_e32 v68, v68, v136
	global_load_lds_dwordx4 v70, s[26:27]
	v_add_u32_e32 v70, v70, v138
	s_cbranch_vccnz .Lmla_fast_nodma_c0
	s_add_i32 m0, s34, 0x6000
	s_nop 0
	global_load_lds_dwordx4 v72, s[26:27]
	v_add_u32_e32 v72, v72, v140
.Lmla_fast_nodma_c0:
	s_waitcnt lgkmcnt(0)
	v_mfma_f32_32x32x16_bf16 v[50:65], v[194:197], v[74:77], v[234:249]
	ds_read_b128 v[194:197], v198 offset:6656
	v_add_f32_e32 v254, v202, v203
	v_add_f32_e32 v255, v204, v205
	v_add_f32_e32 v254, v254, v206
	v_add_f32_e32 v255, v255, v207
	v_add_f32_e32 v254, v254, v208
	v_add_f32_e32 v255, v255, v209
	v_mfma_f32_32x32x16_bf16 v[50:65], v[150:153], v[78:81], v[50:65]
	ds_read_b128 v[150:153], v198 offset:6688
	v_add_f32_e32 v254, v254, v210
	v_add_f32_e32 v255, v255, v211
	v_add_f32_e32 v254, v254, v212
	v_add_f32_e32 v255, v255, v213
	v_add_f32_e32 v254, v254, v214
	v_add_f32_e32 v255, v255, v215
	v_mfma_f32_32x32x16_bf16 v[50:65], v[158:161], v[82:85], v[50:65]
	ds_read_b128 v[158:161], v198 offset:6720
	v_add_f32_e32 v254, v254, v216
	v_add_f32_e32 v255, v255, v217
	v_add_f32_e32 v254, v254, v218
	v_add_f32_e32 v255, v255, v219
	v_add_f32_e32 v254, v254, v220
	v_mfma_f32_32x32x16_bf16 v[50:65], v[162:165], v[86:89], v[50:65]
	ds_read_b128 v[162:165], v198 offset:6752
	v_add_f32_e32 v255, v255, v221
	v_add_f32_e32 v254, v254, v222
	v_add_f32_e32 v255, v255, v223
	v_add_f32_e32 v254, v254, v224
	v_add_f32_e32 v255, v255, v225
	v_mfma_f32_32x32x16_bf16 v[50:65], v[174:177], v[90:93], v[50:65]
	ds_read_b128 v[174:177], v198 offset:6784
	v_add_f32_e32 v254, v254, v226
	v_add_f32_e32 v255, v255, v227
	v_add_f32_e32 v254, v254, v228
	v_add_f32_e32 v255, v255, v229
	v_add_f32_e32 v254, v254, v230
	v_mfma_f32_32x32x16_bf16 v[50:65], v[178:181], v[94:97], v[50:65]
	ds_read_b128 v[178:181], v198 offset:6816
	v_add_f32_e32 v255, v255, v231
	v_add_f32_e32 v254, v254, v232
	v_add_f32_e32 v255, v255, v233
	v_add_f32_e32 v254, v254, v255
	v_add_f32_e32 v147, v147, v254
	v_cmp_lt_f32_e32 vcc, 0x44800000, v254
	s_waitcnt lgkmcnt(5)
	v_mfma_f32_32x32x16_bf16 v[34:49], v[194:197], v[74:77], v[234:249]
	ds_read_b64_tr_b16 v[126:127], v200
	ds_read_b64_tr_b16 v[128:129], v200 offset:1536
	ds_read_b64_tr_b16 v[124:125], v200 offset:1600
	ds_read_b64_tr_b16 v[122:123], v200 offset:64
	s_waitcnt lgkmcnt(8)
	v_mfma_f32_32x32x16_bf16 v[34:49], v[150:153], v[78:81], v[34:49]
	ds_read_b64_tr_b16 v[118:119], v200 offset:3072
	ds_read_b64_tr_b16 v[120:121], v200 offset:4608
	ds_read_b64_tr_b16 v[116:117], v200 offset:4672
	ds_read_b64_tr_b16 v[114:115], v200 offset:3136
	v_exp_f32_e32 v202, v50
	v_exp_f32_e32 v203, v51
	v_exp_f32_e32 v204, v52
	s_waitcnt lgkmcnt(11)
	v_mfma_f32_32x32x16_bf16 v[34:49], v[158:161], v[82:85], v[34:49]
	ds_read_b64_tr_b16 v[110:111], v200 offset:6144
	ds_read_b64_tr_b16 v[112:113], v200 offset:7680
	ds_read_b64_tr_b16 v[108:109], v200 offset:7744
	ds_read_b64_tr_b16 v[106:107], v200 offset:6208
	v_exp_f32_e32 v205, v53
	v_exp_f32_e32 v206, v54
	v_exp_f32_e32 v207, v55
	s_waitcnt lgkmcnt(11)
	v_mfma_f32_32x32x16_bf16 v[34:49], v[162:165], v[86:89], v[34:49]
	ds_read_b64_tr_b16 v[102:103], v200 offset:9216
	ds_read_b64_tr_b16 v[104:105], v200 offset:10752
	ds_read_b64_tr_b16 v[100:101], v200 offset:10816
	ds_read_b64_tr_b16 v[98:99], v200 offset:9280
	v_exp_f32_e32 v208, v56
	v_exp_f32_e32 v209, v57
	v_exp_f32_e32 v210, v58
	v_mfma_f32_32x32x16_bf16 v[34:49], v[174:177], v[90:93], v[34:49]
	v_exp_f32_e32 v211, v59
	v_exp_f32_e32 v212, v60
	v_exp_f32_e32 v213, v61
	v_exp_f32_e32 v214, v62
	v_mfma_f32_32x32x16_bf16 v[34:49], v[178:181], v[94:97], v[34:49]

.Lmla_fast_ok_c0:
	v_cvt_pk_bf16_f32 v166, v202, v203
	v_cvt_pk_bf16_f32 v167, v204, v205
	v_cvt_pk_bf16_f32 v168, v206, v207
	v_cvt_pk_bf16_f32 v169, v208, v209
	s_waitcnt lgkmcnt(0)
	s_nop 0
	v_mfma_f32_32x32x16_bf16 v[18:33], v[126:129], v[166:169], v[18:33]
	v_mfma_f32_32x32x16_bf16 v[2:17], v[122:125], v[166:169], v[2:17]
	v_cvt_pk_bf16_f32 v170, v210, v211
	v_cvt_pk_bf16_f32 v171, v212, v213
	v_cvt_pk_bf16_f32 v172, v214, v215
	v_cvt_pk_bf16_f32 v173, v216, v217
	v_exp_f32_e32 v218, v34
	v_exp_f32_e32 v219, v35
	v_mfma_f32_32x32x16_bf16 v[18:33], v[118:121], v[170:173], v[18:33]
	v_exp_f32_e32 v220, v36
	v_exp_f32_e32 v221, v37
	ds_read_b128 v[194:197], v199
	ds_read_b128 v[150:153], v199 offset:32
	v_mfma_f32_32x32x16_bf16 v[2:17], v[114:117], v[170:173], v[2:17]
	v_exp_f32_e32 v222, v38
	v_exp_f32_e32 v223, v39
	v_exp_f32_e32 v224, v40
	v_exp_f32_e32 v225, v41
	v_cvt_pk_bf16_f32 v166, v218, v219
	v_cvt_pk_bf16_f32 v167, v220, v221
	v_cvt_pk_bf16_f32 v168, v222, v223
	v_cvt_pk_bf16_f32 v169, v224, v225
	ds_read_b128 v[158:161], v199 offset:64
	ds_read_b128 v[162:165], v199 offset:96
	v_mfma_f32_32x32x16_bf16 v[18:33], v[110:113], v[166:169], v[18:33]
	v_exp_f32_e32 v226, v42
	v_exp_f32_e32 v227, v43
	v_exp_f32_e32 v228, v44
	v_mfma_f32_32x32x16_bf16 v[2:17], v[106:109], v[166:169], v[2:17]
	v_exp_f32_e32 v229, v45
	v_exp_f32_e32 v230, v46
	v_exp_f32_e32 v231, v47
	v_exp_f32_e32 v232, v48
	v_exp_f32_e32 v233, v49
	ds_read_b128 v[174:177], v199 offset:128
	ds_read_b128 v[178:181], v199 offset:160
	v_cvt_pk_bf16_f32 v170, v226, v227
	v_cvt_pk_bf16_f32 v171, v228, v229
	v_cvt_pk_bf16_f32 v172, v230, v231
	v_cvt_pk_bf16_f32 v173, v232, v233
	s_add_i32 s30, s30, 1
	s_add_i32 s31, s31, 64
	s_cmp_le_u32 s31, s4
	v_mfma_f32_32x32x16_bf16 v[18:33], v[102:105], v[170:173], v[18:33]
	v_mfma_f32_32x32x16_bf16 v[2:17], v[98:101], v[170:173], v[2:17]
	s_cbranch_scc0 .Lmla_fast_generic
.Lmla_fast_havek_c1:
.Lmla_fast_nodma_c1:
	s_waitcnt lgkmcnt(0)
	v_mfma_f32_32x32x16_bf16 v[50:65], v[194:197], v[74:77], v[234:249]
	ds_read_b128 v[194:197], v199 offset:6656
	v_add_f32_e32 v254, v202, v203
	v_add_f32_e32 v255, v204, v205
	v_add_f32_e32 v254, v254, v206
	v_add_f32_e32 v255, v255, v207
	v_add_f32_e32 v254, v254, v208
	v_add_f32_e32 v255, v255, v209
	v_mfma_f32_32x32x16_bf16 v[50:65], v[150:153], v[78:81], v[50:65]
	ds_read_b128 v[150:153], v199 offset:6688
	v_add_f32_e32 v254, v254, v210
	v_add_f32_e32 v255, v255, v211
	v_add_f32_e32 v254, v254, v212
	v_add_f32_e32 v255, v255, v213
	v_add_f32_e32 v254, v254, v214
	v_add_f32_e32 v255, v255, v215
	v_mfma_f32_32x32x16_bf16 v[50:65], v[158:161], v[82:85], v[50:65]
	ds_read_b128 v[158:161], v199 offset:6720
	v_add_f32_e32 v254, v254, v216
	v_add_f32_e32 v255, v255, v217
	v_add_f32_e32 v254, v254, v218
	v_add_f32_e32 v255, v255, v219
	v_add_f32_e32 v254, v254, v220
	v_mfma_f32_32x32x16_bf16 v[50:65], v[162:165], v[86:89], v[50:65]
	ds_read_b128 v[162:165], v199 offset:6752
	v_add_f32_e32 v255, v255, v221
	v_add_f32_e32 v254, v254, v222
	v_add_f32_e32 v255, v255, v223
	v_add_f32_e32 v254, v254, v224
	v_add_f32_e32 v255, v255, v225
	v_mfma_f32_32x32x16_bf16 v[50:65], v[174:177], v[90:93], v[50:65]
	ds_read_b128 v[174:177], v199 offset:6784
	v_add_f32_e32 v254, v254, v226
	v_add_f32_e32 v255, v255, v227
	v_add_f32_e32 v254, v254, v228
	v_add_f32_e32 v255, v255, v229
	v_add_f32_e32 v254, v254, v230
	v_mfma_f32_32x32x16_bf16 v[50:65], v[178:181], v[94:97], v[50:65]
	ds_read_b128 v[178:181], v199 offset:6816
	v_add_f32_e32 v255, v255, v231
	v_add_f32_e32 v254, v254, v232
	v_add_f32_e32 v255, v255, v233
	v_add_f32_e32 v254, v254, v255
	v_add_f32_e32 v147, v147, v254
	v_cmp_lt_f32_e32 vcc, 0x44800000, v254
	s_waitcnt lgkmcnt(5)
	v_mfma_f32_32x32x16_bf16 v[34:49], v[194:197], v[74:77], v[234:249]
	ds_read_b64_tr_b16 v[126:127], v201
	ds_read_b64_tr_b16 v[128:129], v201 offset:1536
	ds_read_b64_tr_b16 v[124:125], v201 offset:1600
	ds_read_b64_tr_b16 v[122:123], v201 offset:64
	s_waitcnt lgkmcnt(8)
	v_mfma_f32_32x32x16_bf16 v[34:49], v[150:153], v[78:81], v[34:49]
	ds_read_b64_tr_b16 v[118:119], v201 offset:3072
	ds_read_b64_tr_b16 v[120:121], v201 offset:4608
	ds_read_b64_tr_b16 v[116:117], v201 offset:4672
	ds_read_b64_tr_b16 v[114:115], v201 offset:3136
	v_exp_f32_e32 v202, v50
	v_exp_f32_e32 v203, v51
	v_exp_f32_e32 v204, v52
	s_waitcnt lgkmcnt(11)
	v_mfma_f32_32x32x16_bf16 v[34:49], v[158:161], v[82:85], v[34:49]
	ds_read_b64_tr_b16 v[110:111], v201 offset:6144
	ds_read_b64_tr_b16 v[112:113], v201 offset:7680
	ds_read_b64_tr_b16 v[108:109], v201 offset:7744
	ds_read_b64_tr_b16 v[106:107], v201 offset:6208
	v_exp_f32_e32 v205, v53
	v_exp_f32_e32 v206, v54
	v_exp_f32_e32 v207, v55
	s_waitcnt lgkmcnt(11)
	v_mfma_f32_32x32x16_bf16 v[34:49], v[162:165], v[86:89], v[34:49]
	ds_read_b64_tr_b16 v[102:103], v201 offset:9216
	ds_read_b64_tr_b16 v[104:105], v201 offset:10752
	ds_read_b64_tr_b16 v[100:101], v201 offset:10816
	ds_read_b64_tr_b16 v[98:99], v201 offset:9280
	v_exp_f32_e32 v208, v56
	v_exp_f32_e32 v209, v57
	v_exp_f32_e32 v210, v58
	v_mfma_f32_32x32x16_bf16 v[34:49], v[174:177], v[90:93], v[34:49]
	v_exp_f32_e32 v211, v59
	v_exp_f32_e32 v212, v60
	v_exp_f32_e32 v213, v61
	v_exp_f32_e32 v214, v62
	v_mfma_f32_32x32x16_bf16 v[34:49], v[178:181], v[94:97], v[34:49]
	s_waitcnt vmcnt(0) lgkmcnt(0)
	s_barrier

.Lmla_fast_ok_c1:
	v_cvt_pk_bf16_f32 v166, v202, v203
	v_cvt_pk_bf16_f32 v167, v204, v205
	v_cvt_pk_bf16_f32 v168, v206, v207
	v_cvt_pk_bf16_f32 v169, v208, v209
	s_waitcnt lgkmcnt(0)
	s_nop 0
	v_mfma_f32_32x32x16_bf16 v[18:33], v[126:129], v[166:169], v[18:33]
	v_mfma_f32_32x32x16_bf16 v[2:17], v[122:125], v[166:169], v[2:17]
	v_cvt_pk_bf16_f32 v170, v210, v211
	v_cvt_pk_bf16_f32 v171, v212, v213
	v_cvt_pk_bf16_f32 v172, v214, v215
	v_cvt_pk_bf16_f32 v173, v216, v217
	v_exp_f32_e32 v218, v34
	v_exp_f32_e32 v219, v35
	v_mfma_f32_32x32x16_bf16 v[18:33], v[118:121], v[170:173], v[18:33]
	v_exp_f32_e32 v220, v36
	v_exp_f32_e32 v221, v37
	ds_read_b128 v[194:197], v198 offset:51200
	ds_read_b128 v[150:153], v198 offset:51232
	v_mfma_f32_32x32x16_bf16 v[2:17], v[114:117], v[170:173], v[2:17]
	v_exp_f32_e32 v222, v38
	v_exp_f32_e32 v223, v39
	v_exp_f32_e32 v224, v40
	v_exp_f32_e32 v225, v41
	v_cvt_pk_bf16_f32 v166, v218, v219
	v_cvt_pk_bf16_f32 v167, v220, v221
	v_cvt_pk_bf16_f32 v168, v222, v223
	v_cvt_pk_bf16_f32 v169, v224, v225
	ds_read_b128 v[158:161], v198 offset:51264
	ds_read_b128 v[162:165], v198 offset:51296
	v_mfma_f32_32x32x16_bf16 v[18:33], v[110:113], v[166:169], v[18:33]
	v_exp_f32_e32 v226, v42
	v_exp_f32_e32 v227, v43
	v_exp_f32_e32 v228, v44
	v_mfma_f32_32x32x16_bf16 v[2:17], v[106:109], v[166:169], v[2:17]
	v_exp_f32_e32 v229, v45
	v_exp_f32_e32 v230, v46
	v_exp_f32_e32 v231, v47
	v_exp_f32_e32 v232, v48
	v_exp_f32_e32 v233, v49
	ds_read_b128 v[174:177], v198 offset:51328
	ds_read_b128 v[178:181], v198 offset:51360
	v_cvt_pk_bf16_f32 v170, v226, v227
	v_cvt_pk_bf16_f32 v171, v228, v229
	v_cvt_pk_bf16_f32 v172, v230, v231
	v_cvt_pk_bf16_f32 v173, v232, v233
	s_add_i32 s30, s30, 1
	s_add_i32 s31, s31, 64
	s_cmp_le_u32 s31, s4
	v_mfma_f32_32x32x16_bf16 v[18:33], v[102:105], v[170:173], v[18:33]
	v_mfma_f32_32x32x16_bf16 v[2:17], v[98:101], v[170:173], v[2:17]
	s_cbranch_scc0 .Lmla_fast_generic
.Lmla_fast_havek_c2:
	s_add_i32 s34, s30, 2
	s_cmp_gt_u32 s34, s14
	s_cbranch_scc1 .Lmla_fast_d2_c2
	s_mov_b32 s34, 0x0
	s_add_i32 s8, s34, s5
	s_mov_b32 m0, s8
	s_and_b64 vcc, exec, s[36:37]
	global_load_lds_dwordx4 v66, s[26:27]
	s_add_i32 m0, s8, 0x2000
	v_add_u32_e32 v66, v66, v134
	global_load_lds_dwordx4 v68, s[26:27]
	s_add_i32 m0, s8, 0x4000
	v_add_u32_e32 v68, v68, v136
	global_load_lds_dwordx4 v70, s[26:27]
	v_add_u32_e32 v70, v70, v138
	s_cbranch_vccnz .Lmla_fast_d2_c2
	s_add_i32 m0, s34, 0x6000
	s_nop 0
	global_load_lds_dwordx4 v72, s[26:27]
	v_add_u32_e32 v72, v72, v140
.Lmla_fast_d2_c2:
	s_cmp_gt_u32 s30, s13
	s_cbranch_scc1 .Lmla_fast_nodma_c2
	s_mov_b32 s34, 0x6400
	s_add_i32 s8, s34, s5
	s_mov_b32 m0, s8
	s_and_b64 vcc, exec, s[36:37]
	global_load_lds_dwordx4 v66, s[26:27]
	s_add_i32 m0, s8, 0x2000
	v_add_u32_e32 v66, v66, v134
	global_load_lds_dwordx4 v68, s[26:27]
	s_add_i32 m0, s8, 0x4000
	v_add_u32_e32 v68, v68, v136
	global_load_lds_dwordx4 v70, s[26:27]
	v_add_u32_e32 v70, v70, v138
	s_cbranch_vccnz .Lmla_fast_nodma_c2
	s_add_i32 m0, s34, 0x6000
	s_nop 0
	global_load_lds_dwordx4 v72, s[26:27]
	v_add_u32_e32 v72, v72, v140
.Lmla_fast_nodma_c2:
	s_waitcnt lgkmcnt(0)
	v_mfma_f32_32x32x16_bf16 v[50:65], v[194:197], v[74:77], v[234:249]
	ds_read_b128 v[194:197], v198 offset:57856
	v_add_f32_e32 v254, v202, v203
	v_add_f32_e32 v255, v204, v205
	v_add_f32_e32 v254, v254, v206
	v_add_f32_e32 v255, v255, v207
	v_add_f32_e32 v254, v254, v208
	v_add_f32_e32 v255, v255, v209
	v_mfma_f32_32x32x16_bf16 v[50:65], v[150:153], v[78:81], v[50:65]
	ds_read_b128 v[150:153], v198 offset:57888
	v_add_f32_e32 v254, v254, v210
	v_add_f32_e32 v255, v255, v211
	v_add_f32_e32 v254, v254, v212
	v_add_f32_e32 v255, v255, v213
	v_add_f32_e32 v254, v254, v214
	v_add_f32_e32 v255, v255, v215
	v_mfma_f32_32x32x16_bf16 v[50:65], v[158:161], v[82:85], v[50:65]
	ds_read_b128 v[158:161], v198 offset:57920
	v_add_f32_e32 v254, v254, v216
	v_add_f32_e32 v255, v255, v217
	v_add_f32_e32 v254, v254, v218
	v_add_f32_e32 v255, v255, v219
	v_add_f32_e32 v254, v254, v220
	v_mfma_f32_32x32x16_bf16 v[50:65], v[162:165], v[86:89], v[50:65]
	ds_read_b128 v[162:165], v198 offset:57952
	v_add_f32_e32 v255, v255, v221
	v_add_f32_e32 v254, v254, v222
	v_add_f32_e32 v255, v255, v223
	v_add_f32_e32 v254, v254, v224
	v_add_f32_e32 v255, v255, v225
	v_mfma_f32_32x32x16_bf16 v[50:65], v[174:177], v[90:93], v[50:65]
	ds_read_b128 v[174:177], v198 offset:57984
	v_add_f32_e32 v254, v254, v226
	v_add_f32_e32 v255, v255, v227
	v_add_f32_e32 v254, v254, v228
	v_add_f32_e32 v255, v255, v229
	v_add_f32_e32 v254, v254, v230
	v_mfma_f32_32x32x16_bf16 v[50:65], v[178:181], v[94:97], v[50:65]
	ds_read_b128 v[178:181], v198 offset:58016
	v_add_f32_e32 v255, v255, v231
	v_add_f32_e32 v254, v254, v232
	v_add_f32_e32 v255, v255, v233
	v_add_f32_e32 v254, v254, v255
	v_add_f32_e32 v147, v147, v254
	v_cmp_lt_f32_e32 vcc, 0x44800000, v254
	s_waitcnt lgkmcnt(5)
	v_mfma_f32_32x32x16_bf16 v[34:49], v[194:197], v[74:77], v[234:249]
	ds_read_b64_tr_b16 v[126:127], v200 offset:51200
	ds_read_b64_tr_b16 v[128:129], v200 offset:52736
	ds_read_b64_tr_b16 v[124:125], v200 offset:52800
	ds_read_b64_tr_b16 v[122:123], v200 offset:51264
	s_waitcnt lgkmcnt(8)
	v_mfma_f32_32x32x16_bf16 v[34:49], v[150:153], v[78:81], v[34:49]
	ds_read_b64_tr_b16 v[118:119], v200 offset:54272
	ds_read_b64_tr_b16 v[120:121], v200 offset:55808
	ds_read_b64_tr_b16 v[116:117], v200 offset:55872
	ds_read_b64_tr_b16 v[114:115], v200 offset:54336
	v_exp_f32_e32 v202, v50
	v_exp_f32_e32 v203, v51
	v_exp_f32_e32 v204, v52
	s_waitcnt lgkmcnt(11)
	v_mfma_f32_32x32x16_bf16 v[34:49], v[158:161], v[82:85], v[34:49]
	ds_read_b64_tr_b16 v[110:111], v200 offset:57344
	ds_read_b64_tr_b16 v[112:113], v200 offset:58880
	ds_read_b64_tr_b16 v[108:109], v200 offset:58944
	ds_read_b64_tr_b16 v[106:107], v200 offset:57408
	v_exp_f32_e32 v205, v53
	v_exp_f32_e32 v206, v54
	v_exp_f32_e32 v207, v55
	s_waitcnt lgkmcnt(11)
	v_mfma_f32_32x32x16_bf16 v[34:49], v[162:165], v[86:89], v[34:49]
	ds_read_b64_tr_b16 v[102:103], v200 offset:60416
	ds_read_b64_tr_b16 v[104:105], v200 offset:61952
	ds_read_b64_tr_b16 v[100:101], v200 offset:62016
	ds_read_b64_tr_b16 v[98:99], v200 offset:60480
	v_exp_f32_e32 v208, v56
	v_exp_f32_e32 v209, v57
	v_exp_f32_e32 v210, v58
	v_mfma_f32_32x32x16_bf16 v[34:49], v[174:177], v[90:93], v[34:49]
	v_exp_f32_e32 v211, v59
	v_exp_f32_e32 v212, v60
	v_exp_f32_e32 v213, v61
	v_exp_f32_e32 v214, v62
	v_mfma_f32_32x32x16_bf16 v[34:49], v[178:181], v[94:97], v[34:49]

.Lmla_fast_ok_c2:
	v_cvt_pk_bf16_f32 v166, v202, v203
	v_cvt_pk_bf16_f32 v167, v204, v205
	v_cvt_pk_bf16_f32 v168, v206, v207
	v_cvt_pk_bf16_f32 v169, v208, v209
	s_waitcnt lgkmcnt(0)
	s_nop 0
	v_mfma_f32_32x32x16_bf16 v[18:33], v[126:129], v[166:169], v[18:33]
	v_mfma_f32_32x32x16_bf16 v[2:17], v[122:125], v[166:169], v[2:17]
	v_cvt_pk_bf16_f32 v170, v210, v211
	v_cvt_pk_bf16_f32 v171, v212, v213
	v_cvt_pk_bf16_f32 v172, v214, v215
	v_cvt_pk_bf16_f32 v173, v216, v217
	v_exp_f32_e32 v218, v34
	v_exp_f32_e32 v219, v35
	v_mfma_f32_32x32x16_bf16 v[18:33], v[118:121], v[170:173], v[18:33]
	v_exp_f32_e32 v220, v36
	v_exp_f32_e32 v221, v37
	ds_read_b128 v[194:197], v199 offset:51200
	ds_read_b128 v[150:153], v199 offset:51232
	v_mfma_f32_32x32x16_bf16 v[2:17], v[114:117], v[170:173], v[2:17]
	v_exp_f32_e32 v222, v38
	v_exp_f32_e32 v223, v39
	v_exp_f32_e32 v224, v40
	v_exp_f32_e32 v225, v41
	v_cvt_pk_bf16_f32 v166, v218, v219
	v_cvt_pk_bf16_f32 v167, v220, v221
	v_cvt_pk_bf16_f32 v168, v222, v223
	v_cvt_pk_bf16_f32 v169, v224, v225
	ds_read_b128 v[158:161], v199 offset:51264
	ds_read_b128 v[162:165], v199 offset:51296
	v_mfma_f32_32x32x16_bf16 v[18:33], v[110:113], v[166:169], v[18:33]
	v_exp_f32_e32 v226, v42
	v_exp_f32_e32 v227, v43
	v_exp_f32_e32 v228, v44
	v_mfma_f32_32x32x16_bf16 v[2:17], v[106:109], v[166:169], v[2:17]
	v_exp_f32_e32 v229, v45
	v_exp_f32_e32 v230, v46
	v_exp_f32_e32 v231, v47
	v_exp_f32_e32 v232, v48
	v_exp_f32_e32 v233, v49
	ds_read_b128 v[174:177], v199 offset:51328
	ds_read_b128 v[178:181], v199 offset:51360
	v_cvt_pk_bf16_f32 v170, v226, v227
	v_cvt_pk_bf16_f32 v171, v228, v229
	v_cvt_pk_bf16_f32 v172, v230, v231
	v_cvt_pk_bf16_f32 v173, v232, v233
	s_add_i32 s30, s30, 1
	s_add_i32 s31, s31, 64
	s_cmp_le_u32 s31, s4
	v_mfma_f32_32x32x16_bf16 v[18:33], v[102:105], v[170:173], v[18:33]
	v_mfma_f32_32x32x16_bf16 v[2:17], v[98:101], v[170:173], v[2:17]
	s_cbranch_scc0 .Lmla_fast_generic
.Lmla_fast_havek_c3:
.Lmla_fast_nodma_c3:
	s_waitcnt lgkmcnt(0)
	v_mfma_f32_32x32x16_bf16 v[50:65], v[194:197], v[74:77], v[234:249]
	ds_read_b128 v[194:197], v199 offset:57856
	v_add_f32_e32 v254, v202, v203
	v_add_f32_e32 v255, v204, v205
	v_add_f32_e32 v254, v254, v206
	v_add_f32_e32 v255, v255, v207
	v_add_f32_e32 v254, v254, v208
	v_add_f32_e32 v255, v255, v209
	v_mfma_f32_32x32x16_bf16 v[50:65], v[150:153], v[78:81], v[50:65]
	ds_read_b128 v[150:153], v199 offset:57888
	v_add_f32_e32 v254, v254, v210
	v_add_f32_e32 v255, v255, v211
	v_add_f32_e32 v254, v254, v212
	v_add_f32_e32 v255, v255, v213
	v_add_f32_e32 v254, v254, v214
	v_add_f32_e32 v255, v255, v215
	v_mfma_f32_32x32x16_bf16 v[50:65], v[158:161], v[82:85], v[50:65]
	ds_read_b128 v[158:161], v199 offset:57920
	v_add_f32_e32 v254, v254, v216
	v_add_f32_e32 v255, v255, v217
	v_add_f32_e32 v254, v254, v218
	v_add_f32_e32 v255, v255, v219
	v_add_f32_e32 v254, v254, v220
	v_mfma_f32_32x32x16_bf16 v[50:65], v[162:165], v[86:89], v[50:65]
	ds_read_b128 v[162:165], v199 offset:57952
	v_add_f32_e32 v255, v255, v221
	v_add_f32_e32 v254, v254, v222
	v_add_f32_e32 v255, v255, v223
	v_add_f32_e32 v254, v254, v224
	v_add_f32_e32 v255, v255, v225
	v_mfma_f32_32x32x16_bf16 v[50:65], v[174:177], v[90:93], v[50:65]
	ds_read_b128 v[174:177], v199 offset:57984
	v_add_f32_e32 v254, v254, v226
	v_add_f32_e32 v255, v255, v227
	v_add_f32_e32 v254, v254, v228
	v_add_f32_e32 v255, v255, v229
	v_add_f32_e32 v254, v254, v230
	v_mfma_f32_32x32x16_bf16 v[50:65], v[178:181], v[94:97], v[50:65]
	ds_read_b128 v[178:181], v199 offset:58016
	v_add_f32_e32 v255, v255, v231
	v_add_f32_e32 v254, v254, v232
	v_add_f32_e32 v255, v255, v233
	v_add_f32_e32 v254, v254, v255
	v_add_f32_e32 v147, v147, v254
	v_cmp_lt_f32_e32 vcc, 0x44800000, v254
	s_waitcnt lgkmcnt(5)
	v_mfma_f32_32x32x16_bf16 v[34:49], v[194:197], v[74:77], v[234:249]
	ds_read_b64_tr_b16 v[126:127], v201 offset:51200
	ds_read_b64_tr_b16 v[128:129], v201 offset:52736
	ds_read_b64_tr_b16 v[124:125], v201 offset:52800
	ds_read_b64_tr_b16 v[122:123], v201 offset:51264
	s_waitcnt lgkmcnt(8)
	v_mfma_f32_32x32x16_bf16 v[34:49], v[150:153], v[78:81], v[34:49]
	ds_read_b64_tr_b16 v[118:119], v201 offset:54272
	ds_read_b64_tr_b16 v[120:121], v201 offset:55808
	ds_read_b64_tr_b16 v[116:117], v201 offset:55872
	ds_read_b64_tr_b16 v[114:115], v201 offset:54336
	v_exp_f32_e32 v202, v50
	v_exp_f32_e32 v203, v51
	v_exp_f32_e32 v204, v52
	s_waitcnt lgkmcnt(11)
	v_mfma_f32_32x32x16_bf16 v[34:49], v[158:161], v[82:85], v[34:49]
	ds_read_b64_tr_b16 v[110:111], v201 offset:57344
	ds_read_b64_tr_b16 v[112:113], v201 offset:58880
	ds_read_b64_tr_b16 v[108:109], v201 offset:58944
	ds_read_b64_tr_b16 v[106:107], v201 offset:57408
	v_exp_f32_e32 v205, v53
	v_exp_f32_e32 v206, v54
	v_exp_f32_e32 v207, v55
	s_waitcnt lgkmcnt(11)
	v_mfma_f32_32x32x16_bf16 v[34:49], v[162:165], v[86:89], v[34:49]
	ds_read_b64_tr_b16 v[102:103], v201 offset:60416
	ds_read_b64_tr_b16 v[104:105], v201 offset:61952
	ds_read_b64_tr_b16 v[100:101], v201 offset:62016
	ds_read_b64_tr_b16 v[98:99], v201 offset:60480
	v_exp_f32_e32 v208, v56
	v_exp_f32_e32 v209, v57
	v_exp_f32_e32 v210, v58
	v_mfma_f32_32x32x16_bf16 v[34:49], v[174:177], v[90:93], v[34:49]
	v_exp_f32_e32 v211, v59
	v_exp_f32_e32 v212, v60
	v_exp_f32_e32 v213, v61
	v_exp_f32_e32 v214, v62
	v_mfma_f32_32x32x16_bf16 v[34:49], v[178:181], v[94:97], v[34:49]
	s_waitcnt vmcnt(0) lgkmcnt(0)
	s_barrier

.Lmla_fast_ok_c3:
	v_cvt_pk_bf16_f32 v166, v202, v203
	v_cvt_pk_bf16_f32 v167, v204, v205
	v_cvt_pk_bf16_f32 v168, v206, v207
	v_cvt_pk_bf16_f32 v169, v208, v209
	s_waitcnt lgkmcnt(0)
	s_nop 0
	v_mfma_f32_32x32x16_bf16 v[18:33], v[126:129], v[166:169], v[18:33]
	v_mfma_f32_32x32x16_bf16 v[2:17], v[122:125], v[166:169], v[2:17]
	v_cvt_pk_bf16_f32 v170, v210, v211
	v_cvt_pk_bf16_f32 v171, v212, v213
	v_cvt_pk_bf16_f32 v172, v214, v215
	v_cvt_pk_bf16_f32 v173, v216, v217
	v_exp_f32_e32 v218, v34
	v_exp_f32_e32 v219, v35
	v_mfma_f32_32x32x16_bf16 v[18:33], v[118:121], v[170:173], v[18:33]
	v_exp_f32_e32 v220, v36
	v_exp_f32_e32 v221, v37
	ds_read_b128 v[194:197], v198
	ds_read_b128 v[150:153], v198 offset:32
	v_mfma_f32_32x32x16_bf16 v[2:17], v[114:117], v[170:173], v[2:17]
	v_exp_f32_e32 v222, v38
	v_exp_f32_e32 v223, v39
	v_exp_f32_e32 v224, v40
	v_exp_f32_e32 v225, v41
	v_cvt_pk_bf16_f32 v166, v218, v219
	v_cvt_pk_bf16_f32 v167, v220, v221
	v_cvt_pk_bf16_f32 v168, v222, v223
	v_cvt_pk_bf16_f32 v169, v224, v225
	ds_read_b128 v[158:161], v198 offset:64
	ds_read_b128 v[162:165], v198 offset:96
	v_mfma_f32_32x32x16_bf16 v[18:33], v[110:113], v[166:169], v[18:33]
	v_exp_f32_e32 v226, v42
	v_exp_f32_e32 v227, v43
	v_exp_f32_e32 v228, v44
	v_mfma_f32_32x32x16_bf16 v[2:17], v[106:109], v[166:169], v[2:17]
	v_exp_f32_e32 v229, v45
	v_exp_f32_e32 v230, v46
	v_exp_f32_e32 v231, v47
	v_exp_f32_e32 v232, v48
	v_exp_f32_e32 v233, v49
	ds_read_b128 v[174:177], v198 offset:128
	ds_read_b128 v[178:181], v198 offset:160
	v_cvt_pk_bf16_f32 v170, v226, v227
	v_cvt_pk_bf16_f32 v171, v228, v229
	v_cvt_pk_bf16_f32 v172, v230, v231
	v_cvt_pk_bf16_f32 v173, v232, v233
	s_add_i32 s30, s30, 1
	s_add_i32 s31, s31, 64
	s_cmp_le_u32 s31, s4
	v_mfma_f32_32x32x16_bf16 v[18:33], v[102:105], v[170:173], v[18:33]
	v_mfma_f32_32x32x16_bf16 v[2:17], v[98:101], v[170:173], v[2:17]
	s_cbranch_scc1 .Lmla_fast_havek_c0
	s_branch .Lmla_fast_generic
